# attention: qb0 lse/prev loads hoisted ahead of the next-item prefetch so qb0 no longer drains it; counted wait at item top
# baseline (speedup 1.0000x reference)
; __device__ __forceinline__ void phase_attn(const h16* Pda, h16* ob, float* lse, int pat, unsigned char* ldsb) {
;     ...
;     const int lane = tid & 63, w = __builtin_amdgcn_readfirstlane(tid >> 6), fr = lane & 15, g = lane >> 4;
;     const int r = (pat == 0) ? 1 : (pat == 1 ? 4 : 16);
;     const int nbk2 = 16 / r;
;     h16* Ks = (h16*)ldsb;
;     h16* Vs = Ks + 384 * 72;
;     h16* Qs = Vs + 384 * 72;
;     h16x8 pk[6], pv[6], pq[4];
;     ...
;     const int G_ = (int)gridDim.x;
;     if (bid < 1536) ATT_LOAD(bid);
;     for (int item = bid; item < 1536; item += G_) {
;         {
;         {
;         const int mitem = ATT_MAP(item);
;         const int b = mitem / 192, rem = mitem % 192, h = rem / 16, rest = rem % 16;
;         const int p = rest / nbk2, nbA = 2 * (rest % nbk2);
; #pragma unroll
;         for (int it = 0; it < 6; ++it) {
;             const int c = tid + 512 * it, j = c >> 3, part = c & 7;
;             *(h16x8*)(Ks + j * 72 + part * 8) = pk[it];
;             *(h16x8*)(Vs + j * 72 + part * 8) = pv[it];
;         }
; #pragma unroll
;         for (int it = 0; it < 4; ++it) {
;             const int c = tid + 512 * it, i = c >> 3, part = c & 7;
;             *(h16x8*)(Qs + i * 72 + part * 8) = pq[it] * (h16)0.18033688f;
;         }
;         LDS_BARRIER();
;         if (item + G_ < 1536) ATT_LOAD(item + G_);
; #pragma unroll
;         for (int qb = 0; qb < 2; ++qb) {
;         const int nb = nbA + qb;
;         const h16* Kb = Ks + 128 * qb * 72; const h16* Vb = Vs + 128 * qb * 72; const h16* Qb = Qs + 128 * qb * 72;
;         float lp_pre = 0.f; h16x4 prev_pre[4];
; #pragma unroll
;         for (int dt = 0; dt < 4; ++dt) prev_pre[dt] = (h16x4){0, 0, 0, 0};
;         if (pat > 0) {
;             const unsigned tok_ = (unsigned)b * SEQ + p + r * (128 * nb + 16 * w + fr);
;             lp_pre = gld(lse + tok_ * 12 + h);
; #pragma unroll
;             for (int dt = 0; dt < 4; ++dt) prev_pre[dt] = gld((const h16x4*)(ob + tok_ * 768 + h * 64 + 4 * g + 16 * dt));
;         }
;         const float slope = __builtin_amdgcn_exp2f(-8.0f * (float)(h + 1) / 12.0f);
;         const float sr = slope * (float)r * 1.4426950408889634f;
;         h16x8 qf[2];
; #pragma unroll
;         for (int kk = 0; kk < 2; ++kk) qf[kk] = *(const h16x8*)(Qb + (16 * w + fr) * 72 + 32 * kk + 8 * g);
;         float sc[9][4];
;         float mx = -1e30f;
.LBB0_446:
	s_andn2_b64 vcc, exec, s[8:9]
	s_cbranch_vccnz .LBB0_525
	s_ashr_i32 s54, s12, 6
	s_and_b64 s[8:9], s[4:5], exec
	s_cselect_b32 s10, 4, 16
	s_and_b64 s[8:9], s[6:7], exec
	s_cselect_b32 s8, 1, s10
	s_and_b64 s[4:5], s[4:5], exec
	s_cselect_b32 s53, 2, 4
	s_and_b64 s[4:5], s[6:7], exec
	v_and_b32_e32 v34, 63, v99
	s_cselect_b32 s55, 0, s53
	s_cmp_lt_u32 s3, 2
	s_cselect_b64 s[4:5], -1, 0
	v_cmp_gt_u32_e32 vcc, 16, v34
	s_and_b64 s[26:27], s[4:5], vcc
	s_cmp_lt_i32 s54, 16
	s_cselect_b64 s[28:29], -1, 0
	s_cmp_gt_i32 s54, 7
	s_cselect_b64 s[30:31], -1, 0
	s_add_i32 s3, s54, 1
	s_cmp_lt_i32 s54, 15
	s_cselect_b64 s[92:93], -1, 0
	s_cmp_gt_i32 s54, 6
	s_cselect_b64 s[96:97], -1, 0
	s_add_i32 s18, s54, 2
	s_movk_i32 s25, 0x90
	v_lshlrev_b32_e32 v73, 2, v34
	v_lshrrev_b32_e32 v34, 3, v99
	s_cmp_lt_i32 s54, 14
	v_mul_lo_u32 v135, v34, s25
	v_add_u32_e32 v34, 0x200, v99
	s_cselect_b64 s[22:23], -1, 0
	s_cmp_gt_i32 s54, 5
	v_lshrrev_b32_e32 v34, 3, v34
	s_cselect_b64 s[20:21], -1, 0
	s_add_i32 s19, s54, 3
	v_mul_lo_u32 v137, v34, s25
	v_add_u32_e32 v34, 0x400, v99
	s_cmp_lt_i32 s54, 13
	v_and_b32_e32 v35, 15, v99
	v_lshrrev_b32_e32 v34, 3, v34
	s_cselect_b64 s[88:89], -1, 0
	s_cmp_gt_i32 s54, 4
	v_lshlrev_b32_e32 v32, 4, v99
	v_lshl_or_b32 v130, s54, 4, v35
	v_mul_lo_u32 v139, v34, s25
	v_add_u32_e32 v34, 0x600, v99
	s_cselect_b64 s[6:7], -1, 0
	s_add_i32 s24, s54, 4
	v_and_b32_e32 v69, 0x70, v32
	v_readlane_b32 s9, v254, 40
	v_mul_lo_u32 v131, v130, s25
	v_lshrrev_b32_e32 v34, 3, v34
	s_cmp_lt_i32 s54, 12
	v_add_u32_e32 v32, 0, v69
	v_add_u32_e32 v128, s9, v69
	v_cvt_f32_ubyte0_e32 v129, s8
	v_add_u32_e32 v69, s9, v131
	v_mul_lo_u32 v141, v34, s25
	v_add_u32_e32 v34, 0x800, v99
	s_cselect_b64 s[8:9], -1, 0
	s_cmp_gt_i32 s54, 3
	v_lshrrev_b32_e32 v34, 3, v34
	s_cselect_b64 s[10:11], -1, 0
	s_add_i32 s76, s54, 5
	v_mad_u64_u32 v[84:85], s[4:5], v34, s25, v[32:33]
	v_add_u32_e32 v34, 0xa00, v99
	s_cmp_lt_i32 s54, 11
	v_lshrrev_b32_e32 v34, 3, v34
	s_cselect_b64 s[12:13], -1, 0
	s_cmp_gt_i32 s54, 2
	v_lshrrev_b32_e32 v72, 2, v99
	v_mad_u64_u32 v[86:87], s[4:5], v34, s25, v[32:33]
	s_cselect_b64 s[14:15], -1, 0
	s_add_i32 s77, s54, 6
	v_and_b32_e32 v34, 12, v72
	v_readlane_b32 s4, v255, 25
	s_cmp_lt_i32 s54, 10
	v_add_u32_e32 v136, v32, v135
	v_add_u32_e32 v138, v32, v137
	v_add_u32_e32 v140, v32, v139
	v_add_u32_e32 v142, v32, v141
	v_lshlrev_b32_e32 v32, 1, v34
	v_readlane_b32 s5, v255, 26
	s_cselect_b64 s[16:17], -1, 0
	s_cmp_gt_i32 s54, 1
	v_or_b32_e32 v71, 0x80, v35
	v_lshl_add_u64 v[88:89], s[4:5], 0, v[32:33]
	v_or_b32_e32 v32, 1, v34
	s_cselect_b64 s[94:95], -1, 0
	s_add_i32 s78, s54, 7
	v_sub_u32_e32 v72, v71, v32
	v_cmp_lt_u32_e64 s[64:65], v32, v35
	v_lshl_or_b32 v32, s3, 4, v35
	s_cmp_lt_i32 s54, 9
	v_mul_lo_u32 v85, v32, s25
	v_lshl_or_b32 v32, s18, 4, v35
	s_cselect_b64 s[68:69], -1, 0
	s_cmp_gt_i32 s54, 0
	v_mul_lo_u32 v87, v32, s25
	v_lshl_or_b32 v32, s19, 4, v35
	s_cselect_b64 s[70:71], -1, 0
	s_add_i32 s79, s54, 8
	v_mul_lo_u32 v143, v32, s25
	v_lshl_or_b32 v32, s24, 4, v35
	s_cmp_lt_i32 s54, 8
	v_mul_lo_u32 v144, v32, s25
	v_lshl_or_b32 v32, s76, 4, v35
	s_cselect_b64 s[72:73], -1, 0
	s_cmp_gt_i32 s54, -1
	v_sub_u32_e32 v74, v71, v34
	v_mul_lo_u32 v145, v32, s25
	v_lshl_or_b32 v32, s77, 4, v35
	s_cselect_b64 s[56:57], -1, 0
	s_min_i32 s80, s54, 15
	v_xor_b32_e32 v133, 64, v73
	v_xor_b32_e32 v134, 0x80, v73
	v_bfe_u32 v73, v99, 2, 2
	v_cvt_f32_ubyte0_e32 v90, v74
	v_cvt_f32_ubyte0_e32 v91, v72
	v_or_b32_e32 v72, 3, v34
	v_or_b32_e32 v74, 2, v34
	v_mul_lo_u32 v146, v32, s25
	v_lshl_or_b32 v32, s78, 4, v35
	s_min_i32 s3, s3, 15
	s_lshl_b32 s80, s80, 4
	v_cmp_lt_u32_e64 s[4:5], v34, v35
	v_cmp_lt_u32_e64 s[66:67], v74, v35
	v_cmp_lt_u32_e64 s[60:61], v72, v35
	v_mul_lo_u32 v147, v32, s25
	v_lshl_or_b32 v32, s79, 4, v35
	v_cmp_gt_u32_e64 s[62:63], v34, v35
	v_cmp_gt_u32_e64 s[58:59], v72, v35
	v_cmp_gt_u32_e64 s[48:49], v74, v35
	v_or3_b32 v35, s80, v73, v34
	s_lshl_b32 s3, s3, 4
	v_mul_lo_u32 v150, v35, s25
	v_or3_b32 v35, s3, v73, v34
	s_min_i32 s3, s18, 15
	s_min_i32 s18, s19, 15
	s_lshl_b32 s3, s3, 4
	v_mul_lo_u32 v151, v35, s25
	v_or3_b32 v35, s3, v73, v34
	s_lshl_b32 s3, s18, 4
	v_mul_lo_u32 v152, v35, s25
	v_or3_b32 v35, s3, v73, v34
	s_min_i32 s3, s24, 15
	s_min_i32 s18, s76, 15
	s_lshl_b32 s3, s3, 4
	v_mul_lo_u32 v153, v35, s25
	v_or3_b32 v35, s3, v73, v34
	s_lshl_b32 s3, s18, 4
	v_mul_lo_u32 v154, v35, s25
	v_or3_b32 v35, s3, v73, v34
	s_min_i32 s3, s77, 15
	s_min_i32 s18, s78, 15
	s_lshl_b32 s3, s3, 4
	v_mul_lo_u32 v155, v35, s25
	v_or3_b32 v35, s3, v73, v34
	s_lshl_b32 s3, s18, 4
	v_mul_lo_u32 v156, v35, s25
	v_or3_b32 v35, s3, v73, v34
	s_min_i32 s3, s79, 15
	s_min_i32 s18, s54, 6
	s_lshl_b32 s3, s3, 4
	v_mul_lo_u32 v157, v35, s25
	v_or3_b32 v35, s3, v73, v34
	s_lshl_b32 s3, s18, 4
	v_lshlrev_b32_e32 v68, 3, v99
	s_addk_i32 s3, 0x90
	v_mul_lo_u32 v148, v32, s25
	v_and_b32_e32 v32, 24, v68
	v_or3_b32 v34, s3, v73, v34
	s_add_i32 s3, 0, 0x12000
	v_add_u32_e32 v149, 0, v32
	v_add_u32_e32 v160, s3, v32
	v_cvt_f32_ubyte0_e32 v32, s75
	v_rcp_iflag_f32_e32 v32, v32
	s_sub_i32 s3, 0, s75
	v_and_b32_e32 v70, 48, v99
	v_sub_u32_e32 v75, v71, v74
	v_mul_f32_e32 v32, 0x4f7ffffe, v32
	v_cvt_u32_f32_e32 v32, v32
	v_sub_u32_e32 v71, v71, v72
	v_add_u32_e32 v132, 0, v70
	v_cvt_f32_ubyte0_e32 v93, v71
	v_readfirstlane_b32 s18, v32
	s_mul_i32 s3, s3, s18
	s_mul_hi_u32 s3, s18, s3
	v_cvt_f32_ubyte0_e32 v92, v75
	v_mul_lo_u32 v158, v35, s25
	v_mul_lo_u32 v159, v34, s25
	s_add_i32 s50, s18, s3
	v_add_u32_e32 v161, v69, v70
	s_waitcnt vmcnt(0)
	s_branch .LBB0_449
.Lattp_noA:
	s_waitcnt vmcnt(0)
	s_branch .LBB0_463

; #define LDS_BARRIER() do { asm volatile("s_waitcnt lgkmcnt(0)" ::: "memory"); __builtin_amdgcn_s_barrier(); asm volatile("" ::: "memory"); } while (0)
; __device__ __forceinline__ void phase_attn(const h16* Pda, h16* ob, float* lse, int pat, unsigned char* ldsb) {
;     ...
; #pragma unroll
;         for (int it = 0; it < 6; ++it) {
;             const int c = tid + 512 * it, j = c >> 3, part = c & 7;
;             *(h16x8*)(Ks + j * 72 + part * 8) = pk[it];
;             *(h16x8*)(Vs + j * 72 + part * 8) = pv[it];
;         }
; #pragma unroll
;         for (int it = 0; it < 4; ++it) {
;             const int c = tid + 512 * it, i = c >> 3, part = c & 7;
;             *(h16x8*)(Qs + i * 72 + part * 8) = pq[it] * (h16)0.18033688f;
;         }
;         LDS_BARRIER();
;         if (item + G_ < 1536) ATT_LOAD(item + G_);
; #pragma unroll
;         for (int qb = 0; qb < 2; ++qb) {
;         const int nb = nbA + qb;
;         const h16* Kb = Ks + 128 * qb * 72; const h16* Vb = Vs + 128 * qb * 72; const h16* Qb = Qs + 128 * qb * 72;
;         float lp_pre = 0.f; h16x4 prev_pre[4];
; #pragma unroll
;         for (int dt = 0; dt < 4; ++dt) prev_pre[dt] = (h16x4){0, 0, 0, 0};
;         if (pat > 0) {
;             const unsigned tok_ = (unsigned)b * SEQ + p + r * (128 * nb + 16 * w + fr);
;             lp_pre = gld(lse + tok_ * 12 + h);
; #pragma unroll
;             for (int dt = 0; dt < 4; ++dt) prev_pre[dt] = gld((const h16x4*)(ob + tok_ * 768 + h * 64 + 4 * g + 16 * dt));
;         }
.LBB0_449:
	s_movk_i32 s3, 0x31c5
	s_waitcnt vmcnt(4)
	v_pk_mul_f16 v71, v55, s3 op_sel_hi:[1,0]
	v_pk_mul_f16 v70, v54, s3 op_sel_hi:[1,0]
	v_pk_mul_f16 v69, v53, s3 op_sel_hi:[1,0]
	v_pk_mul_f16 v68, v52, s3 op_sel_hi:[1,0]
	v_add_u32_e32 v32, v128, v135
	ds_write_b128 v136, v[8:11]
	ds_write_b128 v136, v[4:7] offset:55296
	ds_write_b128 v138, v[0:3]
	ds_write_b128 v138, v[12:15] offset:55296
	ds_write_b128 v140, v[20:23]
	ds_write_b128 v140, v[16:19] offset:55296
	ds_write_b128 v142, v[28:31]
	ds_write_b128 v142, v[24:27] offset:55296
	ds_write_b128 v84, v[40:43]
	ds_write_b128 v84, v[36:39] offset:55296
	ds_write_b128 v86, v[48:51]
	ds_write_b128 v86, v[44:47] offset:55296
	ds_write_b128 v32, v[68:71]
	v_pk_mul_f16 v71, v59, s3 op_sel_hi:[1,0]
	v_pk_mul_f16 v70, v58, s3 op_sel_hi:[1,0]
	v_pk_mul_f16 v69, v57, s3 op_sel_hi:[1,0]
	v_pk_mul_f16 v68, v56, s3 op_sel_hi:[1,0]
	v_add_u32_e32 v32, v128, v137
	ds_write_b128 v32, v[68:71]
	v_pk_mul_f16 v71, v63, s3 op_sel_hi:[1,0]
	v_pk_mul_f16 v70, v62, s3 op_sel_hi:[1,0]
	v_pk_mul_f16 v69, v61, s3 op_sel_hi:[1,0]
	v_pk_mul_f16 v68, v60, s3 op_sel_hi:[1,0]
	v_add_u32_e32 v32, v128, v139
	ds_write_b128 v32, v[68:71]
	v_pk_mul_f16 v71, v67, s3 op_sel_hi:[1,0]
	v_pk_mul_f16 v70, v66, s3 op_sel_hi:[1,0]
	v_pk_mul_f16 v69, v65, s3 op_sel_hi:[1,0]
	v_pk_mul_f16 v68, v64, s3 op_sel_hi:[1,0]
	v_add_u32_e32 v32, v128, v141
	ds_write_b128 v32, v[68:71]
	s_add_i32 s3, s35, s34
	s_waitcnt lgkmcnt(0)
	s_barrier
	s_mov_b32 s98, s35
	v_mov_b32_e32 v223, 0
	v_readlane_b32 s0, v255, 36
	v_readlane_b32 s1, v255, 37
	s_and_b32 s18, s98, 7
	s_mulk_i32 s18, 0xc0
	s_ashr_i32 s19, s98, 3
	s_add_i32 s18, s18, s19
	s_mul_hi_i32 s19, s18, 0x2aaaaaab
	s_lshr_b32 s24, s19, 31
	s_ashr_i32 s19, s19, 5
	s_add_i32 s19, s19, s24
	s_mul_i32 s24, s19, 0xc0
	s_sub_i32 s24, s18, s24
	s_bfe_u32 s18, s24, 0x4001b
	s_add_i32 s98, s24, s18
	s_sext_i32_i16 s78, s98
	s_and_b32 s98, s98, 0xfff0
	s_sub_i32 s24, s24, s98
	s_sext_i32_i16 s24, s24
	s_abs_i32 s79, s24
	s_mul_hi_u32 s80, s79, s50
	s_mul_i32 s81, s80, s75
	s_sub_i32 s79, s79, s81
	s_lshr_b32 s18, s78, 4
	s_ashr_i32 s98, s24, 31
	s_add_i32 s81, s80, 1
	s_sub_i32 vcc_lo, s79, s75
	s_cmp_ge_u32 s79, s75
	s_cselect_b32 s80, s81, s80
	s_cselect_b32 s79, vcc_lo, s79
	s_add_i32 s81, s80, 1
	s_cmp_ge_u32 s79, s75
	s_cselect_b32 s79, s81, s80
	s_xor_b32 s79, s79, s98
	s_sub_i32 s79, s79, s98
	s_mul_i32 s98, s79, s75
	s_ashr_i32 s80, s78, 4
	s_lshl_b32 s19, s19, 12
	s_sub_i32 s98, s24, s98
	s_add_i32 s24, s79, s19
	s_lshl_b32 s78, s80, 6
	s_bfe_i64 s[18:19], s[18:19], 0x100000
	s_ashr_i32 s79, s78, 31
	s_lshl_b64 s[18:19], s[18:19], 2
	v_readlane_b32 s25, v255, 32
	v_lshl_add_u64 v[224:225], s[78:79], 1, v[88:89]
	s_add_u32 s78, s25, s18
	v_readlane_b32 s18, v255, 35
	v_cndmask_b32_e64 v222, 0, 1, s[0:1]
	s_addc_u32 s79, s18, s19
	v_cmp_ne_u32_e64 s[18:19], 1, v222
	s_andn2_b64 vcc, exec, s[0:1]
	v_lshl_add_u32 v230, s98, 8, v130
	s_cbranch_vccnz .Lattp_skip
	v_lshlrev_b32_e32 v222, s53, v230
	v_add_u32_e32 v228, s24, v222
	v_mul_lo_u32 v222, v228, 12
	s_movk_i32 s25, 0x300
	v_lshl_add_u64 v[226:227], v[222:223], 2, s[78:79]
	v_mul_lo_u32 v222, v228, s25
	v_lshl_add_u64 v[228:229], v[222:223], 1, v[224:225]
	global_load_dword v204, v[226:227], off
	global_load_dwordx2 v[206:207], v[228:229], off
	global_load_dwordx2 v[208:209], v[228:229], off offset:32
	global_load_dwordx2 v[210:211], v[228:229], off offset:64
	global_load_dwordx2 v[212:213], v[228:229], off offset:96
.Lattp_skip:
	s_cmpk_gt_i32 s3, 0x5ff
	s_cselect_b64 s[76:77], -1, 0
	s_and_b64 vcc, exec, s[76:77]
	s_cbranch_vccnz .Lattp_noA
	s_and_b32 s18, s3, 7
	s_mulk_i32 s18, 0xc0
	s_ashr_i32 s19, s3, 3
	s_add_i32 s18, s18, s19
	s_mul_hi_i32 s19, s18, 0x2aaaaaab
	s_lshr_b32 s24, s19, 31
	s_ashr_i32 s19, s19, 5
	s_add_i32 s19, s19, s24
	s_mul_i32 s24, s19, 0xc0
	s_sub_i32 s18, s18, s24
	s_bfe_u32 s24, s18, 0x4001b
	s_add_i32 s24, s18, s24
	s_sext_i32_i16 s80, s24
	s_and_b32 s24, s24, 0xfff0
	s_sub_i32 s18, s18, s24
	s_sext_i32_i16 s18, s18
	s_abs_i32 s78, s18
	s_mul_hi_u32 s79, s78, s50
	s_mul_i32 s81, s79, s75
	s_sub_i32 s78, s78, s81
	s_ashr_i32 s24, s18, 31
	s_add_i32 s81, s79, 1
	s_sub_i32 vcc_lo, s78, s75
	s_cmp_ge_u32 s78, s75
	s_mov_b64 s[0:1], s[48:49]
	s_mov_b32 s74, s50
	s_cselect_b32 s79, s81, s79
	v_readlane_b32 s36, v254, 43
	s_cselect_b32 s78, vcc_lo, s78
	s_add_i32 s81, s79, 1
	v_readlane_b32 s37, v254, 44
	v_readlane_b32 s38, v254, 45
	v_readlane_b32 s39, v254, 46
	v_readlane_b32 s40, v254, 47
	v_readlane_b32 s41, v254, 48
	v_readlane_b32 s42, v254, 49
	v_readlane_b32 s43, v254, 50
	v_readlane_b32 s44, v254, 51
	v_readlane_b32 s45, v254, 52
	v_readlane_b32 s46, v254, 53
	v_readlane_b32 s47, v254, 54
	v_readlane_b32 s48, v254, 55
	v_readlane_b32 s49, v254, 56
	v_readlane_b32 s50, v254, 57
	v_readlane_b32 s51, v254, 58
	s_cmp_ge_u32 s78, s75
	s_mov_b32 s25, s45
	v_writelane_b32 v254, s36, 43
	s_cselect_b32 s78, s81, s79
	s_xor_b32 s78, s78, s24
	v_writelane_b32 v254, s37, 44
	v_writelane_b32 v254, s38, 45
	s_sub_i32 s78, s78, s24
	v_writelane_b32 v254, s39, 46
	s_mul_i32 s24, s78, s75
	v_writelane_b32 v254, s40, 47
	s_sub_i32 s18, s18, s24
	s_mul_i32 s24, s19, 0x900000
	v_writelane_b32 v254, s41, 48
	s_lshl_b32 s79, s18, 8
	v_writelane_b32 v254, s42, 49
	s_lshl_b64 s[18:19], s[24:25], 1
	v_writelane_b32 v254, s43, 50
	s_add_u32 s24, s86, s18
	v_writelane_b32 v254, s44, 51
	s_addc_u32 s81, s87, s19
	s_lshl_b32 s18, s80, 2
	v_writelane_b32 v254, s45, 52
	s_andn2_b32 s18, s18, 63
	v_writelane_b32 v254, s46, 53
	s_ashr_i32 s19, s18, 31
	v_writelane_b32 v254, s47, 54
	s_lshl_b64 s[18:19], s[18:19], 1
	v_mov_b32_e32 v44, v99
	v_writelane_b32 v254, s48, 55
	s_add_u32 s18, s24, s18
	v_writelane_b32 v254, s49, 56
	s_addc_u32 s19, s81, s19
	s_add_i32 s24, s79, 0xffffff80
	v_lshlrev_b32_e32 v0, 4, v44
	v_ashrrev_i32_e32 v52, 3, v44
	v_mov_b32_e32 v2, v33
	v_mov_b32_e32 v3, v33
	v_writelane_b32 v254, s50, 57
	v_and_b32_e32 v32, 0x70, v0
	v_add_u32_e32 v12, s24, v52
	v_mov_b32_e32 v0, v33
	v_mov_b32_e32 v1, v33
	v_mov_b64_e32 v[10:11], v[2:3]
	v_mov_b64_e32 v[6:7], v[2:3]
	v_writelane_b32 v254, s51, 58
	v_lshl_add_u64 v[60:61], s[18:19], 0, v[32:33]
	v_cmp_lt_i32_e32 vcc, -1, v12
	v_mov_b64_e32 v[8:9], v[0:1]
	v_mov_b64_e32 v[4:5], v[0:1]
	s_and_saveexec_b64 s[18:19], vcc
	s_cbranch_execz .LBB0_452
	v_lshlrev_b32_e32 v4, s55, v12
	v_add_u32_e32 v4, s78, v4
	s_movk_i32 s25, 0x900
	v_mul_lo_u32 v32, v4, s25
	v_lshl_add_u64 v[4:5], v[32:33], 1, v[60:61]
	global_load_dwordx4 v[8:11], v[4:5], off offset:1536
	s_nop 0
	global_load_dwordx4 v[4:7], v[4:5], off offset:3072

; __device__ __forceinline__ void phase_attn(const h16* Pda, h16* ob, float* lse, int pat, unsigned char* ldsb) {
;     ...
;         const int nb = nbA + qb;
;         const h16* Kb = Ks + 128 * qb * 72; const h16* Vb = Vs + 128 * qb * 72; const h16* Qb = Qs + 128 * qb * 72;
;         float lp_pre = 0.f; h16x4 prev_pre[4];
; #pragma unroll
;         for (int dt = 0; dt < 4; ++dt) prev_pre[dt] = (h16x4){0, 0, 0, 0};
;         if (pat > 0) {
;             const unsigned tok_ = (unsigned)b * SEQ + p + r * (128 * nb + 16 * w + fr);
;             lp_pre = gld(lse + tok_ * 12 + h);
; #pragma unroll
;             for (int dt = 0; dt < 4; ++dt) prev_pre[dt] = gld((const h16x4*)(ob + tok_ * 768 + h * 64 + 4 * g + 16 * dt));
;         }
.LBB0_463:
	s_and_b32 s18, s35, 7
	s_mulk_i32 s18, 0xc0
	s_ashr_i32 s19, s35, 3
	s_add_i32 s18, s18, s19
	s_mul_hi_i32 s19, s18, 0x2aaaaaab
	s_lshr_b32 s24, s19, 31
	s_ashr_i32 s19, s19, 5
	s_add_i32 s19, s19, s24
	s_mul_i32 s24, s19, 0xc0
	s_sub_i32 s24, s18, s24
	s_bfe_u32 s18, s24, 0x4001b
	s_add_i32 s35, s24, s18
	s_sext_i32_i16 s78, s35
	s_and_b32 s35, s35, 0xfff0
	s_sub_i32 s24, s24, s35
	s_sext_i32_i16 s24, s24
	s_abs_i32 s79, s24
	s_mul_hi_u32 s80, s79, s50
	s_mul_i32 s81, s80, s75
	s_sub_i32 s79, s79, s81
	s_lshr_b32 s18, s78, 4
	s_ashr_i32 s35, s24, 31
	s_add_i32 s81, s80, 1
	s_sub_i32 vcc_lo, s79, s75
	s_cmp_ge_u32 s79, s75
	s_cselect_b32 s80, s81, s80
	s_cselect_b32 s79, vcc_lo, s79
	s_add_i32 s81, s80, 1
	s_cmp_ge_u32 s79, s75
	s_cselect_b32 s79, s81, s80
	s_xor_b32 s79, s79, s35
	s_sub_i32 s79, s79, s35
	s_mul_i32 s35, s79, s75
	s_ashr_i32 s80, s78, 4
	s_lshl_b32 s19, s19, 12
	s_sub_i32 s35, s24, s35
	s_add_i32 s24, s79, s19
	s_lshl_b32 s78, s80, 6
	s_bfe_i64 s[18:19], s[18:19], 0x100000
	s_ashr_i32 s79, s78, 31
	s_lshl_b64 s[18:19], s[18:19], 2
	v_readlane_b32 s25, v255, 32
	v_lshl_add_u64 v[34:35], s[78:79], 1, v[88:89]
	s_add_u32 s78, s25, s18
	v_readlane_b32 s18, v255, 35
	v_cndmask_b32_e64 v32, 0, 1, s[0:1]
	s_addc_u32 s79, s18, s19
	v_cmp_ne_u32_e64 s[18:19], 1, v32
	s_andn2_b64 vcc, exec, s[0:1]
	v_lshl_add_u32 v162, s35, 8, v130
	s_cbranch_vccnz .LBB0_465
	v_lshlrev_b32_e32 v32, s53, v162
	v_add_u32_e32 v70, s24, v32
	v_mul_lo_u32 v32, v70, 12
	s_movk_i32 s25, 0x300
	v_lshl_add_u64 v[68:69], v[32:33], 2, s[78:79]
	v_mul_lo_u32 v32, v70, s25
	v_lshl_add_u64 v[70:71], v[32:33], 1, v[34:35]
	s_waitcnt vmcnt(12)
	v_mov_b32_e32 v32, v204
	v_mov_b32_e32 v106, v206
	v_mov_b32_e32 v107, v207
	v_mov_b32_e32 v104, v208
	v_mov_b32_e32 v105, v209
	v_mov_b32_e32 v102, v210
	v_mov_b32_e32 v103, v211
	v_mov_b32_e32 v100, v212
	v_mov_b32_e32 v101, v213
	s_branch .LBB0_466

; __device__ __forceinline__ float shx(float v, int m, int lane) { return __int_as_float(__builtin_amdgcn_ds_bpermute((lane ^ m) << 2, __float_as_int(v))); }
; __device__ __forceinline__ h16x8 cat8(h16x4 a, h16x4 b) { return __builtin_shufflevector(a, b, 0, 1, 2, 3, 4, 5, 6, 7); }
; __device__ __forceinline__ h16x4 tr_read4(const h16* p) { return __builtin_bit_cast(h16x4, __builtin_amdgcn_ds_read_tr16_b64_v4i16((LAS s16x4v*)p)); }
; #define MFMA16(a, b, c) __builtin_amdgcn_mfma_f32_16x16x32_f16((a), (b), (c), 0, 0, 0)
; __device__ __forceinline__ void phase_attn(const h16* Pda, h16* ob, float* lse, int pat, unsigned char* ldsb) {
;     ...
;         mx = fmaxf(mx, shx(mx, 16, lane)); mx = fmaxf(mx, shx(mx, 32, lane));
;         float lsum = 0.f;
; #pragma unroll
;         for (int tt = 0; tt < 9; ++tt)
; #pragma unroll
;             for (int rg = 0; rg < 4; ++rg) { const float pv = __builtin_amdgcn_exp2f(sc[tt][rg] - mx); sc[tt][rg] = pv; lsum += pv; }
;         lsum += shx(lsum, 16, lane); lsum += shx(lsum, 32, lane);
;         f32x4 o[4];
; #pragma unroll
;         for (int dt = 0; dt < 4; ++dt) o[dt] = (f32x4){0.f, 0.f, 0.f, 0.f};
; #pragma unroll
;         for (int kk2 = 0; kk2 < 5; ++kk2) {
;             const int ta = 2 * kk2, tb = 2 * kk2 + 1;
;             h16x8 pf;
; #pragma unroll
;             for (int rg = 0; rg < 4; ++rg) { pf[rg] = (h16)sc[ta][rg]; pf[4 + rg] = (tb <= 8) ? (h16)sc[tb < 9 ? tb : 8][rg] : (h16)0.f; }
;             const int ja = (w + ta) < 15 ? (w + ta) : 15, jb = (w + tb) < 15 ? (w + tb) : 15;
; #pragma unroll
;             for (int dt = 0; dt < 4; ++dt) {
;                 const h16x4 va = tr_read4(Vb + (16 * ja + 4 * g + (fr >> 2)) * 72 + 16 * dt + 4 * (fr & 3));
;                 const h16x4 vb = tr_read4(Vb + (16 * jb + 4 * g + (fr >> 2)) * 72 + 16 * dt + 4 * (fr & 3));
;                 o[dt] = MFMA16(cat8(va, vb), pf, o[dt]);
;             }
;         }
.LBB0_489:
	ds_bpermute_b32 v69, v133, v163
	v_max_f32_e32 v72, v163, v163
	s_waitcnt lgkmcnt(0)
	v_max_f32_e32 v69, v69, v69
	v_max_f32_e32 v69, v72, v69
	ds_bpermute_b32 v72, v134, v69
	s_waitcnt lgkmcnt(0)
	v_max_f32_e32 v72, v72, v72
	v_max_f32_e32 v163, v69, v72
	v_sub_f32_e32 v69, v164, v163
	v_exp_f32_e32 v164, v69
	v_sub_f32_e32 v72, v165, v163
	v_exp_f32_e32 v165, v72
	v_sub_f32_e32 v72, v166, v163
	v_exp_f32_e32 v166, v72
	v_sub_f32_e32 v72, v167, v163
	v_exp_f32_e32 v167, v72
	v_sub_f32_e32 v72, v80, v163
	v_add_f32_e32 v69, 0, v164
	v_exp_f32_e32 v80, v72
	v_sub_f32_e32 v72, v81, v163
	v_add_f32_e32 v69, v165, v69
	v_exp_f32_e32 v81, v72
	v_sub_f32_e32 v72, v76, v163
	v_add_f32_e32 v69, v166, v69
	v_exp_f32_e32 v169, v72
	v_sub_f32_e32 v72, v77, v163
	v_add_f32_e32 v69, v167, v69
	v_exp_f32_e32 v170, v72
	v_sub_f32_e32 v72, v82, v163
	v_add_f32_e32 v69, v80, v69
	v_exp_f32_e32 v171, v72
	v_sub_f32_e32 v72, v83, v163
	v_add_f32_e32 v69, v81, v69
	v_exp_f32_e32 v172, v72
	v_sub_f32_e32 v72, v108, v163
	v_add_f32_e32 v69, v169, v69
	v_exp_f32_e32 v173, v72
	v_sub_f32_e32 v72, v109, v163
	v_add_f32_e32 v69, v170, v69
	v_exp_f32_e32 v174, v72
	v_sub_f32_e32 v72, v110, v163
	v_add_f32_e32 v69, v171, v69
	v_exp_f32_e32 v175, v72
	v_sub_f32_e32 v72, v111, v163
	v_add_f32_e32 v69, v172, v69
	v_exp_f32_e32 v176, v72
	v_sub_f32_e32 v72, v78, v163
	v_add_f32_e32 v69, v173, v69
	v_exp_f32_e32 v177, v72
	v_sub_f32_e32 v72, v79, v163
	v_add_f32_e32 v69, v174, v69
	v_exp_f32_e32 v178, v72
	v_sub_f32_e32 v72, v114, v163
	v_add_f32_e32 v69, v175, v69
	v_exp_f32_e32 v179, v72
	v_sub_f32_e32 v72, v115, v163
	v_add_f32_e32 v69, v176, v69
	v_exp_f32_e32 v180, v72
	v_sub_f32_e32 v72, v116, v163
	v_add_f32_e32 v69, v177, v69
	v_exp_f32_e32 v181, v72
	v_sub_f32_e32 v72, v117, v163
	v_add_f32_e32 v69, v178, v69
	v_exp_f32_e32 v190, v72
	v_sub_f32_e32 v72, v118, v163
	v_add_f32_e32 v69, v179, v69
	v_exp_f32_e32 v191, v72
	v_sub_f32_e32 v72, v119, v163
	v_add_f32_e32 v69, v180, v69
	v_exp_f32_e32 v196, v72
	v_sub_f32_e32 v72, v112, v163
	v_add_f32_e32 v69, v181, v69
	v_exp_f32_e32 v197, v72
	v_sub_f32_e32 v72, v113, v163
	v_add_f32_e32 v69, v190, v69
	v_exp_f32_e32 v198, v72
	v_sub_f32_e32 v72, v122, v163
	v_add_f32_e32 v69, v191, v69
	v_exp_f32_e32 v72, v72
	v_sub_f32_e32 v73, v123, v163
	v_add_f32_e32 v69, v196, v69
	v_exp_f32_e32 v73, v73
	v_sub_f32_e32 v74, v124, v163
	v_add_f32_e32 v69, v197, v69
	v_exp_f32_e32 v74, v74
	v_sub_f32_e32 v75, v125, v163
	v_add_f32_e32 v69, v198, v69
	v_exp_f32_e32 v75, v75
	v_sub_f32_e32 v76, v126, v163
	v_add_f32_e32 v69, v72, v69
	v_exp_f32_e32 v76, v76
	v_sub_f32_e32 v77, v127, v163
	v_add_f32_e32 v69, v73, v69
	v_exp_f32_e32 v77, v77
	v_sub_f32_e32 v78, v120, v163
	v_add_f32_e32 v69, v74, v69
	v_exp_f32_e32 v78, v78
	v_sub_f32_e32 v79, v121, v163
	v_add_f32_e32 v69, v75, v69
	v_exp_f32_e32 v79, v79
	v_sub_f32_e32 v68, v68, v163
	v_add_f32_e32 v69, v76, v69
	v_exp_f32_e32 v68, v68
	v_add_f32_e32 v69, v77, v69
	v_add_f32_e32 v69, v78, v69
	v_add_f32_e32 v69, v79, v69
	v_add_f32_e32 v82, v68, v69
	v_sub_f32_e32 v69, v168, v163
	v_exp_f32_e32 v69, v69
	v_sub_f32_e32 v70, v70, v163
	v_exp_f32_e32 v70, v70
	v_sub_f32_e32 v71, v71, v163
	v_exp_f32_e32 v71, v71
	v_add_f32_e32 v82, v69, v82
	v_add_f32_e32 v82, v70, v82
	v_add_u32_e32 v122, v149, v150
	v_add_f32_e32 v82, v71, v82
	ds_bpermute_b32 v83, v133, v82
	v_add_u32_e32 v124, v149, v151
	ds_read_b64_tr_b16 v[112:113], v124 offset:55296
	ds_read_b64_tr_b16 v[116:117], v124 offset:55328
	ds_read_b64_tr_b16 v[110:111], v122 offset:55296
	ds_read_b64_tr_b16 v[114:115], v122 offset:55328
	ds_read_b64_tr_b16 v[118:119], v122 offset:55360
	ds_read_b64_tr_b16 v[120:121], v124 offset:55360
	ds_read_b64_tr_b16 v[122:123], v122 offset:55392
	ds_read_b64_tr_b16 v[124:125], v124 offset:55392
	s_waitcnt lgkmcnt(8)
	v_add_f32_e32 v108, v82, v83
	v_cvt_pk_f16_f32 v83, v169, v170
	v_cvt_pk_f16_f32 v82, v80, v81
	v_cvt_pk_f16_f32 v81, v166, v167
	v_cvt_pk_f16_f32 v80, v164, v165
	v_add_u32_e32 v127, v149, v153
	v_add_u32_e32 v126, v149, v152
	s_waitcnt lgkmcnt(5)
	v_mfma_f32_16x16x32_f16 v[110:113], v[110:113], v[80:83], 0
	v_cvt_pk_f16_f32 v79, v78, v79
	v_cvt_pk_f16_f32 v78, v76, v77
	v_cvt_pk_f16_f32 v77, v74, v75
	s_waitcnt lgkmcnt(4)
	v_mfma_f32_16x16x32_f16 v[114:117], v[114:117], v[80:83], 0
	v_cvt_pk_f16_f32 v76, v72, v73
	ds_bpermute_b32 v109, v134, v108
	s_waitcnt lgkmcnt(0)
	v_add_f32_e32 v109, v108, v109
	v_mfma_f32_16x16x32_f16 v[118:121], v[118:121], v[80:83], 0
	v_div_scale_f32 v108, s[80:81], v109, v109, 1.0
	v_mfma_f32_16x16x32_f16 v[80:83], v[122:125], v[80:83], 0
	v_cvt_pk_f16_f32 v122, v171, v172
	ds_read_b64_tr_b16 v[166:167], v127 offset:55296
	ds_read_b64_tr_b16 v[170:171], v127 offset:55328
	ds_read_b64_tr_b16 v[164:165], v126 offset:55296
	ds_read_b64_tr_b16 v[168:169], v126 offset:55328
	v_cvt_pk_f16_f32 v125, v177, v178
	v_cvt_pk_f16_f32 v124, v175, v176
	v_cvt_pk_f16_f32 v123, v173, v174
	s_waitcnt lgkmcnt(1)
	s_nop 0
	v_mfma_f32_16x16x32_f16 v[110:113], v[164:167], v[122:125], v[110:113]
	ds_read_b64_tr_b16 v[164:165], v126 offset:55360
	ds_read_b64_tr_b16 v[166:167], v127 offset:55360
	s_waitcnt lgkmcnt(0)
	v_mfma_f32_16x16x32_f16 v[118:121], v[164:167], v[122:125], v[118:121]
	ds_read_b64_tr_b16 v[164:165], v126 offset:55392
	ds_read_b64_tr_b16 v[166:167], v127 offset:55392
	v_add_u32_e32 v127, v149, v155
	v_add_u32_e32 v126, v149, v154
	v_mfma_f32_16x16x32_f16 v[114:117], v[168:171], v[122:125], v[114:117]
	s_waitcnt lgkmcnt(0)
; __device__ __forceinline__ float fexp(float x) { return __builtin_amdgcn_exp2f(x * 1.4426950408889634f); }
; __device__ __forceinline__ float flog(float x) { return __builtin_amdgcn_logf(x) * 0.6931471805599453f; }
; __device__ __forceinline__ h16x8 cat8(h16x4 a, h16x4 b) { return __builtin_shufflevector(a, b, 0, 1, 2, 3, 4, 5, 6, 7); }
; __device__ __forceinline__ h16x4 tr_read4(const h16* p) { return __builtin_bit_cast(h16x4, __builtin_amdgcn_ds_read_tr16_b64_v4i16((LAS s16x4v*)p)); }
; #define MFMA16(a, b, c) __builtin_amdgcn_mfma_f32_16x16x32_f16((a), (b), (c), 0, 0, 0)
; __device__ __forceinline__ void phase_attn(const h16* Pda, h16* ob, float* lse, int pat, unsigned char* ldsb) {
;     ...
;             const int ja = (w + ta) < 15 ? (w + ta) : 15, jb = (w + tb) < 15 ? (w + tb) : 15;
; #pragma unroll
;             for (int dt = 0; dt < 4; ++dt) {
;                 const h16x4 va = tr_read4(Vb + (16 * ja + 4 * g + (fr >> 2)) * 72 + 16 * dt + 4 * (fr & 3));
;                 const h16x4 vb = tr_read4(Vb + (16 * jb + 4 * g + (fr >> 2)) * 72 + 16 * dt + 4 * (fr & 3));
;                 o[dt] = MFMA16(cat8(va, vb), pf, o[dt]);
;             }
;         }
;         {
;             const int t = p + r * (128 * nb + iq);
;             const unsigned tok = (unsigned)b * SEQ + t;
;             const float inv = 1.0f / lsum, lse_p = (mx + __builtin_amdgcn_logf(lsum)) * 0.6931471805599453f;
;             float w1 = 0.f, w2 = inv, lse_new = lse_p;
;             if (pat > 0) {
;                 const float lp = lp_pre, m2 = fmaxf(lp, lse_p), e1 = fexp(lp - m2), e2 = fexp(lse_p - m2), den = e1 + e2;
;                 w1 = e1 / den; w2 = e2 * inv / den; lse_new = m2 + flog(den);
;             }
	v_mfma_f32_16x16x32_f16 v[80:83], v[164:167], v[122:125], v[80:83]
	ds_read_b64_tr_b16 v[166:167], v127 offset:55296
	ds_read_b64_tr_b16 v[170:171], v127 offset:55328
	ds_read_b64_tr_b16 v[164:165], v126 offset:55296
	ds_read_b64_tr_b16 v[168:169], v126 offset:55328
	v_cvt_pk_f16_f32 v125, v197, v198
	v_cvt_pk_f16_f32 v124, v191, v196
	v_cvt_pk_f16_f32 v123, v181, v190
	v_cvt_pk_f16_f32 v122, v179, v180
	s_waitcnt lgkmcnt(1)
	s_nop 0
	v_mfma_f32_16x16x32_f16 v[110:113], v[164:167], v[122:125], v[110:113]
	ds_read_b64_tr_b16 v[164:165], v126 offset:55360
	ds_read_b64_tr_b16 v[166:167], v127 offset:55360
	s_waitcnt lgkmcnt(0)
	v_mfma_f32_16x16x32_f16 v[118:121], v[164:167], v[122:125], v[118:121]
	ds_read_b64_tr_b16 v[164:165], v126 offset:55392
	ds_read_b64_tr_b16 v[166:167], v127 offset:55392
	v_add_u32_e32 v127, v149, v157
	v_add_u32_e32 v126, v149, v156
	v_mfma_f32_16x16x32_f16 v[114:117], v[168:171], v[122:125], v[114:117]
	s_waitcnt lgkmcnt(0)
	v_mfma_f32_16x16x32_f16 v[80:83], v[164:167], v[122:125], v[80:83]
	ds_read_b64_tr_b16 v[74:75], v127 offset:55296
	ds_read_b64_tr_b16 v[124:125], v127 offset:55328
	ds_read_b64_tr_b16 v[72:73], v126 offset:55296
	ds_read_b64_tr_b16 v[122:123], v126 offset:55328
	s_waitcnt lgkmcnt(1)
	v_mfma_f32_16x16x32_f16 v[72:75], v[72:75], v[76:79], v[110:113]
	s_waitcnt lgkmcnt(0)
	v_mfma_f32_16x16x32_f16 v[110:113], v[122:125], v[76:79], v[114:117]
	s_nop 2
	ds_read_b64_tr_b16 v[114:115], v126 offset:55360
	ds_read_b64_tr_b16 v[116:117], v127 offset:55360
	v_cvt_pk_f16_f32 v123, v70, v71
	v_cvt_pk_f16_f32 v122, v68, v69
	s_waitcnt lgkmcnt(0)
	v_mfma_f32_16x16x32_f16 v[114:117], v[114:117], v[76:79], v[118:121]
	s_nop 2
	ds_read_b64_tr_b16 v[118:119], v126 offset:55392
	ds_read_b64_tr_b16 v[120:121], v127 offset:55392
	v_add_u32_e32 v127, v149, v159
	v_add_u32_e32 v126, v149, v158
	s_waitcnt lgkmcnt(0)
	v_mfma_f32_16x16x32_f16 v[118:121], v[118:121], v[76:79], v[80:83]
	ds_read_b64_tr_b16 v[70:71], v127 offset:55296
	ds_read_b64_tr_b16 v[78:79], v127 offset:55328
	ds_read_b64_tr_b16 v[68:69], v126 offset:55296
	ds_read_b64_tr_b16 v[76:77], v126 offset:55328
	v_mov_b32_e32 v124, v33
	v_mov_b32_e32 v125, v33
	s_waitcnt lgkmcnt(0)
	s_nop 0
	v_mfma_f32_16x16x32_f16 v[76:79], v[76:79], v[122:125], v[110:113]
	s_nop 2
	v_rcp_f32_e32 v110, v108
	v_mfma_f32_16x16x32_f16 v[80:83], v[68:71], v[122:125], v[72:75]
	ds_read_b64_tr_b16 v[68:69], v126 offset:55360
	ds_read_b64_tr_b16 v[70:71], v127 offset:55360
	v_fma_f32 v111, -v108, v110, 1.0
	v_fmac_f32_e32 v110, v111, v110
	v_div_scale_f32 v111, vcc, 1.0, v109, 1.0
	v_mul_f32_e32 v112, v111, v110
	v_fma_f32 v113, -v108, v112, v111
	s_waitcnt lgkmcnt(0)
	v_mfma_f32_16x16x32_f16 v[72:75], v[68:71], v[122:125], v[114:117]
	ds_read_b64_tr_b16 v[68:69], v126 offset:55392
	ds_read_b64_tr_b16 v[70:71], v127 offset:55392
	v_fmac_f32_e32 v112, v113, v110
	v_fma_f32 v108, -v108, v112, v111
	v_div_fmas_f32 v108, v108, v110, v112
	v_div_fixup_f32 v108, v108, v109, 1.0
	v_log_f32_e32 v109, v109
	s_waitcnt lgkmcnt(0)
	v_mfma_f32_16x16x32_f16 v[68:71], v[68:71], v[122:125], v[118:121]
	s_and_b64 vcc, exec, s[18:19]
	v_add_f32_e32 v109, v163, v109
	v_mul_f32_e32 v109, 0x3f317218, v109
	s_cbranch_vccnz .LBB0_491
	v_max_f32_e32 v110, v109, v109
	s_nop 0
	v_max_f32_e32 v111, v32, v32
	v_max_f32_e32 v111, v111, v110
	v_sub_f32_e32 v32, v32, v111
	v_sub_f32_e32 v109, v109, v111
	v_mul_f32_e32 v32, 0x3fb8aa3b, v32
	v_mul_f32_e32 v109, 0x3fb8aa3b, v109
	v_exp_f32_e32 v32, v32
	v_exp_f32_e32 v109, v109
	s_nop 0
	v_add_f32_e32 v112, v32, v109
	v_div_scale_f32 v110, s[80:81], v112, v112, v32
	v_rcp_f32_e32 v113, v110
	s_nop 0
	v_fma_f32 v114, -v110, v113, 1.0
	v_fmac_f32_e32 v113, v114, v113
	v_div_scale_f32 v114, vcc, v32, v112, v32
	v_mul_f32_e32 v115, v114, v113
	v_fma_f32 v116, -v110, v115, v114
	v_fmac_f32_e32 v115, v116, v113
	v_fma_f32 v110, -v110, v115, v114
	v_div_fmas_f32 v110, v110, v113, v115
	v_div_fixup_f32 v110, v110, v112, v32
	v_mul_f32_e32 v32, v108, v109
	v_div_scale_f32 v108, s[80:81], v112, v112, v32
	v_rcp_f32_e32 v109, v108
	s_nop 0
	v_fma_f32 v113, -v108, v109, 1.0
	v_fmac_f32_e32 v109, v113, v109
	v_div_scale_f32 v113, vcc, v32, v112, v32
	v_mul_f32_e32 v114, v113, v109
	v_fma_f32 v115, -v108, v114, v113
	v_fmac_f32_e32 v114, v115, v109
	v_fma_f32 v108, -v108, v114, v113
	v_div_fmas_f32 v108, v108, v109, v114
	v_div_fixup_f32 v108, v108, v112, v32
	v_log_f32_e32 v32, v112
	s_nop 0
	v_fmac_f32_e32 v111, 0x3f317218, v32
	v_mov_b32_e32 v109, v111
	s_branch .LBB0_492
; __device__ __forceinline__ float fexp(float x) { return __builtin_amdgcn_exp2f(x * 1.4426950408889634f); }
; __device__ __forceinline__ float flog(float x) { return __builtin_amdgcn_logf(x) * 0.6931471805599453f; }
; __device__ __forceinline__ void phase_attn(const h16* Pda, h16* ob, float* lse, int pat, unsigned char* ldsb) {
;     ...
;         {
;             const int t = p + r * (128 * nb + iq);
;             const unsigned tok = (unsigned)b * SEQ + t;
;             const float inv = 1.0f / lsum, lse_p = (mx + __builtin_amdgcn_logf(lsum)) * 0.6931471805599453f;
;             float w1 = 0.f, w2 = inv, lse_new = lse_p;
;             if (pat > 0) {
;                 const float lp = lp_pre, m2 = fmaxf(lp, lse_p), e1 = fexp(lp - m2), e2 = fexp(lse_p - m2), den = e1 + e2;
;                 w1 = e1 / den; w2 = e2 * inv / den; lse_new = m2 + flog(den);
;             }
;             h16* op = ob + tok * 768 + h * 64 + 4 * g;
; #pragma unroll
;             for (int dt = 0; dt < 4; ++dt) {
;                 h16x4 prev = {0, 0, 0, 0};
;                 if (pat > 0) prev = prev_pre[dt];
;                 h16x4 res;
; #pragma unroll
;                 for (int rg = 0; rg < 4; ++rg) res[rg] = (h16)(w1 * (float)prev[rg] + w2 * o[dt][rg]);
;                 gst((h16x4*)(op + 16 * dt), res);
;             }
;             if (pat < 2 && g == 0) gst(lse + tok * 12 + h, lse_new);
.LBB0_491:
	s_nop 0
	v_mov_b32_e32 v100, 0
	v_mov_b32_e32 v110, 0
	v_mov_b32_e32 v101, 0
	v_mov_b32_e32 v102, 0
	v_mov_b32_e32 v103, 0
	v_mov_b32_e32 v104, 0
	v_mov_b32_e32 v105, 0
	v_mov_b32_e32 v106, 0
	v_mov_b32_e32 v107, 0
.LBB0_492:
	s_nop 0
	v_cvt_f32_f16_sdwa v115, v106 dst_sel:DWORD dst_unused:UNUSED_PAD src0_sel:WORD_1
	v_cvt_f32_f16_e32 v114, v106
	v_lshlrev_b32_e32 v32, s55, v162
	v_add_u32_e32 v111, s24, v32
	v_pk_mul_f32 v[80:81], v[80:81], v[108:109] op_sel_hi:[1,0]
	s_movk_i32 s25, 0x300
	v_pk_fma_f32 v[80:81], v[110:111], v[114:115], v[80:81] op_sel_hi:[0,1,1]
	v_cvt_f32_f16_sdwa v115, v107 dst_sel:DWORD dst_unused:UNUSED_PAD src0_sel:WORD_1
	v_cvt_f32_f16_e32 v114, v107
	v_pk_mul_f32 v[82:83], v[82:83], v[108:109] op_sel_hi:[1,0]
	v_mul_lo_u32 v32, v111, s25
	v_lshl_add_u64 v[112:113], v[32:33], 1, v[34:35]
	v_pk_fma_f32 v[82:83], v[110:111], v[114:115], v[82:83] op_sel_hi:[0,1,1]
	v_cvt_pk_f16_f32 v80, v80, v81
	v_cvt_pk_f16_f32 v81, v82, v83
	global_store_dwordx2 v[112:113], v[80:81], off
	s_nop 0
	v_cvt_f32_f16_sdwa v81, v104 dst_sel:DWORD dst_unused:UNUSED_PAD src0_sel:WORD_1
	v_cvt_f32_f16_e32 v80, v104
	v_pk_mul_f32 v[76:77], v[76:77], v[108:109] op_sel_hi:[1,0]
	v_pk_mul_f32 v[78:79], v[78:79], v[108:109] op_sel_hi:[1,0]
	v_pk_mul_f32 v[72:73], v[72:73], v[108:109] op_sel_hi:[1,0]
	v_pk_fma_f32 v[76:77], v[110:111], v[80:81], v[76:77] op_sel_hi:[0,1,1]
	v_cvt_f32_f16_sdwa v81, v105 dst_sel:DWORD dst_unused:UNUSED_PAD src0_sel:WORD_1
	v_cvt_f32_f16_e32 v80, v105
	v_cvt_pk_f16_f32 v76, v76, v77
	v_pk_mul_f32 v[74:75], v[74:75], v[108:109] op_sel_hi:[1,0]
	v_pk_mul_f32 v[68:69], v[68:69], v[108:109] op_sel_hi:[1,0]
	v_pk_fma_f32 v[78:79], v[110:111], v[80:81], v[78:79] op_sel_hi:[0,1,1]
	v_cvt_pk_f16_f32 v77, v78, v79
	global_store_dwordx2 v[112:113], v[76:77], off offset:32
	s_nop 0
	v_cvt_f32_f16_sdwa v77, v102 dst_sel:DWORD dst_unused:UNUSED_PAD src0_sel:WORD_1
	v_cvt_f32_f16_e32 v76, v102
	v_pk_mul_f32 v[70:71], v[70:71], v[108:109] op_sel_hi:[1,0]
	v_pk_fma_f32 v[72:73], v[110:111], v[76:77], v[72:73] op_sel_hi:[0,1,1]
	v_cvt_f32_f16_sdwa v77, v103 dst_sel:DWORD dst_unused:UNUSED_PAD src0_sel:WORD_1
	v_cvt_f32_f16_e32 v76, v103
	v_cvt_pk_f16_f32 v72, v72, v73
	v_pk_fma_f32 v[74:75], v[110:111], v[76:77], v[74:75] op_sel_hi:[0,1,1]
	v_cvt_pk_f16_f32 v73, v74, v75
	global_store_dwordx2 v[112:113], v[72:73], off offset:64
	s_nop 0
	v_cvt_f32_f16_sdwa v73, v100 dst_sel:DWORD dst_unused:UNUSED_PAD src0_sel:WORD_1
	v_cvt_f32_f16_e32 v72, v100
	v_pk_fma_f32 v[68:69], v[110:111], v[72:73], v[68:69] op_sel_hi:[0,1,1]
	v_cvt_f32_f16_sdwa v73, v101 dst_sel:DWORD dst_unused:UNUSED_PAD src0_sel:WORD_1
	v_cvt_f32_f16_e32 v72, v101
	v_cvt_pk_f16_f32 v68, v68, v69
	v_pk_fma_f32 v[70:71], v[110:111], v[72:73], v[70:71] op_sel_hi:[0,1,1]
	v_cvt_pk_f16_f32 v69, v70, v71
	global_store_dwordx2 v[112:113], v[68:69], off offset:96
	s_and_saveexec_b64 s[80:81], s[26:27]
	s_cbranch_execz .LBB0_494
	v_mul_lo_u32 v32, v111, 12
	v_lshl_add_u64 v[68:69], v[32:33], 2, s[78:79]
	global_store_dword v[68:69], v109, off
